# attention: K/V fragment reads hoisted, mp0 DMA issue moved behind last V reads, counted lgkmcnt waits per MFMA
# speedup vs baseline: 1.0236x; 1.0038x over previous
.LBB0_622:
	v_add3_u32 v165, s57, v143, v163
	ds_read_b128 v[190:193], v165 offset:18432
	ds_read_b128 v[194:197], v165 offset:18448
	ds_read_b128 v[128:131], v165 offset:23040
	ds_read_b128 v[132:135], v165 offset:23056
	ds_read_b128 v[136:139], v165 offset:27648
	ds_read_b128 v[166:169], v165 offset:27664
	ds_read_b128 v[170:173], v165 offset:32256
	ds_read_b128 v[178:181], v165 offset:32272
	v_exp_f32_e32 v96, v96
	v_exp_f32_e32 v97, v97
	v_exp_f32_e32 v98, v98
	v_exp_f32_e32 v99, v99
	v_exp_f32_e32 v100, v100
	v_add_f32_e32 v198, v97, v96
	v_exp_f32_e32 v101, v101
	v_add_f32_e32 v198, v98, v198
	v_exp_f32_e32 v102, v102
	v_add_f32_e32 v198, v99, v198
	v_exp_f32_e32 v103, v103
	v_add_f32_e32 v198, v100, v198
	v_exp_f32_e32 v104, v104
	v_add_f32_e32 v198, v101, v198
	v_exp_f32_e32 v105, v105
	v_add_f32_e32 v198, v102, v198
	v_exp_f32_e32 v106, v106
	v_add_f32_e32 v198, v103, v198
	v_exp_f32_e32 v107, v107
	v_add_f32_e32 v198, v104, v198
	v_exp_f32_e32 v108, v108
	v_add_f32_e32 v198, v105, v198
	v_exp_f32_e32 v109, v109
	v_add_f32_e32 v198, v106, v198
	v_exp_f32_e32 v110, v110
	v_add_f32_e32 v198, v107, v198
	v_exp_f32_e32 v111, v111
	v_add_f32_e32 v198, v108, v198
	v_add_f32_e32 v198, v109, v198
	v_add_f32_e32 v198, v110, v198
	v_add_f32_e32 v198, v111, v198
	v_add_f32_e32 v157, v157, v198
	v_cvt_pk_bf16_f32 v96, v96, v97
	v_cvt_pk_bf16_f32 v97, v98, v99
	v_cvt_pk_bf16_f32 v98, v100, v101
	v_cvt_pk_bf16_f32 v99, v102, v103
	v_cvt_pk_bf16_f32 v100, v104, v105
	v_cvt_pk_bf16_f32 v101, v106, v107
	v_cvt_pk_bf16_f32 v102, v108, v109
	v_cvt_pk_bf16_f32 v103, v110, v111
	s_waitcnt lgkmcnt(7)
	v_mfma_f32_32x32x16_bf16 v[48:63], v[190:193], v[96:99], v[48:63]
	v_exp_f32_e32 v174, v80
	v_exp_f32_e32 v175, v81
	v_exp_f32_e32 v182, v82
	v_exp_f32_e32 v183, v83
	v_add_f32_e32 v80, v175, v174
	v_add_f32_e32 v80, v182, v80
	s_waitcnt lgkmcnt(5)
	v_mfma_f32_32x32x16_bf16 v[0:15], v[128:131], v[96:99], v[0:15]
	v_add_f32_e32 v80, v183, v80
	v_mfma_f32_32x32x16_bf16 v[48:63], v[194:197], v[100:103], v[48:63]
	v_exp_f32_e32 v128, v84
	v_exp_f32_e32 v129, v85
	v_exp_f32_e32 v130, v86
	v_exp_f32_e32 v131, v87
	v_add_f32_e32 v80, v128, v80
	v_add_f32_e32 v80, v129, v80
	v_add_f32_e32 v80, v130, v80
	s_waitcnt lgkmcnt(4)
	v_mfma_f32_32x32x16_bf16 v[0:15], v[132:135], v[100:103], v[0:15]
	v_add_f32_e32 v184, v131, v80
	ds_read_b128 v[80:83], v165 offset:18496
	ds_read_b128 v[84:87], v165 offset:18512
	ds_read_b128 v[104:107], v165 offset:23104
	ds_read_b128 v[108:111], v165 offset:23120
	s_waitcnt lgkmcnt(7)
	v_mfma_f32_32x32x16_bf16 v[32:47], v[136:139], v[96:99], v[32:47]
	v_exp_f32_e32 v132, v88
	v_exp_f32_e32 v133, v89
	v_exp_f32_e32 v134, v90
	v_exp_f32_e32 v135, v91
	v_add_f32_e32 v88, v132, v184
	v_add_f32_e32 v88, v133, v88
	v_add_f32_e32 v88, v134, v88
	s_waitcnt lgkmcnt(5)
	v_mfma_f32_32x32x16_bf16 v[16:31], v[170:173], v[96:99], v[16:31]
	v_add_f32_e32 v88, v135, v88
	v_exp_f32_e32 v96, v92
	v_mfma_f32_32x32x16_bf16 v[32:47], v[166:169], v[100:103], v[32:47]
	v_exp_f32_e32 v97, v93
	v_exp_f32_e32 v98, v94
	v_exp_f32_e32 v95, v95
	v_add_f32_e32 v88, v96, v88
	v_add_f32_e32 v88, v97, v88
	v_add_f32_e32 v88, v98, v88
	v_add_f32_e32 v88, v95, v88
	s_waitcnt lgkmcnt(4)
	v_mfma_f32_32x32x16_bf16 v[16:31], v[178:181], v[100:103], v[16:31]
	v_add_f32_e32 v157, v157, v88
	v_cvt_pk_bf16_f32 v88, v174, v175
	v_cvt_pk_bf16_f32 v89, v182, v183
	v_cvt_pk_bf16_f32 v90, v128, v129
	v_cvt_pk_bf16_f32 v91, v130, v131
	v_cvt_pk_bf16_f32 v92, v132, v133
	v_cvt_pk_bf16_f32 v93, v134, v135
	v_cvt_pk_bf16_f32 v94, v96, v97
	v_cvt_pk_bf16_f32 v95, v98, v95
	ds_read_b128 v[96:99], v165 offset:27712
	ds_read_b128 v[100:103], v165 offset:27728
	ds_read_b128 v[128:131], v165 offset:32320
	ds_read_b128 v[132:135], v165 offset:32336
	s_waitcnt lgkmcnt(7)
	v_mfma_f32_32x32x16_bf16 v[48:63], v[80:83], v[88:91], v[48:63]
	s_waitcnt lgkmcnt(5)
	v_mfma_f32_32x32x16_bf16 v[0:15], v[104:107], v[88:91], v[0:15]
	v_mfma_f32_32x32x16_bf16 v[48:63], v[84:87], v[92:95], v[48:63]
	s_waitcnt lgkmcnt(4)
	v_mfma_f32_32x32x16_bf16 v[0:15], v[108:111], v[92:95], v[0:15]
	s_waitcnt lgkmcnt(3)
	v_mfma_f32_32x32x16_bf16 v[32:47], v[96:99], v[88:91], v[32:47]
	s_waitcnt lgkmcnt(1)
	v_mfma_f32_32x32x16_bf16 v[16:31], v[128:131], v[88:91], v[16:31]
	v_mfma_f32_32x32x16_bf16 v[32:47], v[100:103], v[92:95], v[32:47]
	s_waitcnt lgkmcnt(0)
	v_mfma_f32_32x32x16_bf16 v[16:31], v[132:135], v[92:95], v[16:31]
	s_add_i32 s4, s9, 0x9000
	s_cmp_lg_u32 s9, 0x12000
	s_cselect_b32 s9, s4, 0
	s_add_i32 s4, s56, 1
	s_cmp_lg_u32 s56, 2
	s_cselect_b32 s56, s4, 0
	s_add_i32 s8, s8, 1
	s_add_u32 s40, s40, 0x80
	s_addc_u32 s41, s41, 0
	s_add_u32 s46, s46, 0x60000
	s_waitcnt lgkmcnt(0)
	s_barrier
	s_addc_u32 s47, s47, 0
	s_add_i32 s87, s87, 64
	s_cmpk_lg_i32 s87, 0xfc0
	s_cbranch_scc0 .LBB0_633
.LBB0_623:
	s_add_i32 s57, s9, 0
	s_add_i32 s4, s57, s94
	v_add_u32_e32 v80, s4, v162
	v_add_u32_e32 v84, v80, v146
	ds_read_b128 v[80:83], v84
	ds_read_b128 v[128:131], v84 offset:32
	ds_read_b128 v[136:139], v84 offset:4608
	ds_read_b128 v[132:135], v84 offset:4640
	ds_read_b128 v[166:169], v84 offset:64
	ds_read_b128 v[170:173], v84 offset:96
	ds_read_b128 v[178:181], v84 offset:4672
	ds_read_b128 v[182:185], v84 offset:4704
	s_cmp_gt_u32 s8, 61
	s_cselect_b64 s[78:79], -1, 0
	s_and_b64 vcc, exec, s[78:79]
	s_cbranch_vccnz .LBB0_625
	s_mul_i32 s16, s56, 0x9000
	s_add_i32 s17, s16, s35
	s_and_b64 s[80:81], s[54:55], exec
	s_cselect_b32 m0, s17, s82
	s_nop 0
	global_load_lds_dwordx4 v[240:241], off
	s_add_i32 s17, s16, s33
	s_and_b64 s[80:81], s[64:65], exec
	s_cselect_b32 m0, s17, s2
	v_lshl_add_u64 v[240:241], v[240:241], 0, v[200:201]
	global_load_lds_dwordx4 v[242:243], off
	s_add_i32 s17, s16, s93
	s_and_b64 s[80:81], s[42:43], exec
	s_cselect_b32 m0, s17, s92
	v_lshl_add_u64 v[242:243], v[242:243], 0, v[202:203]
	global_load_lds_dwordx4 v[244:245], off
	s_add_i32 s17, s16, s45
	s_and_b64 s[80:81], s[24:25], exec
	s_cselect_b32 m0, s17, s97
	v_lshl_add_u64 v[244:245], v[244:245], 0, v[204:205]
	global_load_lds_dwordx4 v[246:247], off
	s_add_i32 s17, s16, s59
	s_and_b64 s[80:81], s[70:71], exec
	s_cselect_b32 m0, s17, s27
	v_lshl_add_u64 v[246:247], v[246:247], 0, v[206:207]
	global_load_lds_dwordx4 v[248:249], off
	v_lshl_add_u64 v[248:249], v[248:249], 0, v[208:209]
.LBB0_625:
	s_add_i32 s16, s91, s87
	s_add_i32 s4, s16, 64
	s_cmpk_lt_i32 s4, 0xff42
	s_cselect_b32 s5, 1, 0
	s_cmpk_gt_i32 s4, 0x9e
	s_cselect_b32 s4, 2, s5
	s_cmp_eq_u32 s4, s32
	s_cbranch_scc1 .Lattn_negm_keep_0
	s_mov_b32 s32, s4
	s_cmp_eq_u32 s4, 1
	s_cselect_b64 vcc, -1, 0
	s_cmp_eq_u32 s4, 2
	s_cselect_b64 s[4:5], -1, 0
	v_cndmask_b32_e64 v84, 0, v160, s[4:5]
	v_cndmask_b32_e32 v252, v84, v159, vcc
	v_sub_f32_e32 v84, v252, v156
	v_mov_b32_e32 v79, v84
	v_mov_b32_e32 v78, v84
	v_mov_b32_e32 v77, v84
	v_mov_b32_e32 v76, v84
	v_mov_b32_e32 v75, v84
	v_mov_b32_e32 v74, v84
	v_mov_b32_e32 v73, v84
	v_mov_b32_e32 v72, v84
	v_mov_b32_e32 v71, v84
	v_mov_b32_e32 v70, v84
	v_mov_b32_e32 v69, v84
	v_mov_b32_e32 v68, v84
	v_mov_b32_e32 v67, v84
	v_mov_b32_e32 v66, v84
	v_mov_b32_e32 v65, v84
	v_mov_b32_e32 v64, v84
.Lattn_negm_keep_0:
	s_addk_i32 s16, 0xffa1
	s_cmp_lt_u32 s16, 0xfffffea3
	s_nop 0
	s_waitcnt lgkmcnt(7)
	v_mfma_f32_32x32x16_bf16 v[96:111], v[80:83], v[112:115], v[64:79]
	s_waitcnt lgkmcnt(5)
	v_mfma_f32_32x32x16_bf16 v[80:95], v[136:139], v[112:115], v[64:79]
	v_mfma_f32_32x32x16_bf16 v[96:111], v[128:131], v[116:119], v[96:111]
	s_waitcnt lgkmcnt(4)
	v_mfma_f32_32x32x16_bf16 v[80:95], v[132:135], v[116:119], v[80:95]
	s_waitcnt lgkmcnt(3)
	v_mfma_f32_32x32x16_bf16 v[96:111], v[166:169], v[120:123], v[96:111]
	s_waitcnt lgkmcnt(1)
	v_mfma_f32_32x32x16_bf16 v[80:95], v[178:181], v[120:123], v[80:95]
	v_mfma_f32_32x32x16_bf16 v[96:111], v[170:173], v[124:127], v[96:111]
	s_waitcnt lgkmcnt(0)
	v_mfma_f32_32x32x16_bf16 v[80:95], v[182:185], v[124:127], v[80:95]
	s_cbranch_scc1 .LBB0_627
	v_add_u32_e32 v180, s87, v164
	v_max_i32_e32 v130, 0xffffff7f, v180
	v_add_u32_e32 v130, 0x81, v130
	s_add_i32 s80, 0, 0x20000
	v_min_u32_e32 v130, 0x100, v130
	v_lshl_add_u32 v132, v130, 2, s80
	v_max_i32_e32 v130, 0xffffff7e, v180
	v_add_u32_e32 v130, 0x82, v130
	v_max_i32_e32 v138, 0xffffff7b, v180
	v_min_u32_e32 v130, 0x100, v130
	v_add_u32_e32 v138, 0x85, v138
	v_max_i32_e32 v128, 0xffffff80, v180
	v_max_i32_e32 v129, 0xffffff60, v180
	v_max_i32_e32 v131, 0xffffff5f, v180
	v_max_i32_e32 v133, 0xffffff5e, v180
	v_lshl_add_u32 v134, v130, 2, s80
	v_max_i32_e32 v130, 0xffffff7d, v180
	v_max_i32_e32 v135, 0xffffff5d, v180
	v_min_u32_e32 v138, 0x100, v138
	v_add_u32_e32 v128, 0x80, v128
	v_add_u32_e32 v129, 0xa0, v129
	v_add_u32_e32 v131, 0xa1, v131
	v_add_u32_e32 v133, 0xa2, v133
	v_add_u32_e32 v130, 0x83, v130
	v_add_u32_e32 v135, 0xa3, v135
	v_lshl_add_u32 v166, v138, 2, s80
	v_max_i32_e32 v138, 0xffffff7a, v180
	v_min_u32_e32 v128, 0x100, v128
	v_min_u32_e32 v129, 0x100, v129
	v_min_u32_e32 v131, 0x100, v131
	v_min_u32_e32 v133, 0x100, v133
	v_min_u32_e32 v130, 0x100, v130
	v_min_u32_e32 v135, 0x100, v135
	v_add_u32_e32 v138, 0x86, v138
	v_max_i32_e32 v172, 0xffffff77, v180
	v_lshl_add_u32 v128, v128, 2, s80
	v_lshl_add_u32 v129, v129, 2, s80
	v_lshl_add_u32 v131, v131, 2, s80
	v_lshl_add_u32 v133, v133, 2, s80
	v_lshl_add_u32 v136, v130, 2, s80
	v_lshl_add_u32 v135, v135, 2, s80
	v_min_u32_e32 v138, 0x100, v138
	v_add_u32_e32 v172, 0x89, v172
	ds_read_b32 v128, v128
	ds_read_b32 v130, v129
	ds_read_b32 v129, v132
	ds_read_b32 v131, v131
	ds_read_b32 v132, v134
	ds_read_b32 v134, v133
	ds_read_b32 v133, v136
	ds_read_b32 v135, v135
	v_max_i32_e32 v136, 0xffffff7c, v180
	v_max_i32_e32 v137, 0xffffff5c, v180
	v_max_i32_e32 v139, 0xffffff5b, v180
	v_max_i32_e32 v167, 0xffffff5a, v180
	v_lshl_add_u32 v168, v138, 2, s80
	v_max_i32_e32 v138, 0xffffff79, v180
	v_max_i32_e32 v169, 0xffffff59, v180
	v_min_u32_e32 v172, 0x100, v172
	v_add_u32_e32 v136, 0x84, v136
	v_add_u32_e32 v137, 0xa4, v137
	v_add_u32_e32 v139, 0xa5, v139
	v_add_u32_e32 v167, 0xa6, v167
	v_add_u32_e32 v138, 0x87, v138
	v_add_u32_e32 v169, 0xa7, v169
	v_lshl_add_u32 v174, v172, 2, s80
	v_max_i32_e32 v172, 0xffffff76, v180
	v_min_u32_e32 v136, 0x100, v136
	v_min_u32_e32 v137, 0x100, v137
	v_min_u32_e32 v139, 0x100, v139
	v_min_u32_e32 v167, 0x100, v167
	v_min_u32_e32 v138, 0x100, v138
	v_min_u32_e32 v169, 0x100, v169
	v_add_u32_e32 v172, 0x8a, v172
	v_lshl_add_u32 v136, v136, 2, s80
	v_lshl_add_u32 v137, v137, 2, s80
	v_lshl_add_u32 v139, v139, 2, s80
	v_lshl_add_u32 v167, v167, 2, s80
	v_lshl_add_u32 v170, v138, 2, s80
	v_lshl_add_u32 v169, v169, 2, s80
	v_min_u32_e32 v172, 0x100, v172
	ds_read_b32 v136, v136
	ds_read_b32 v138, v137
	ds_read_b32 v137, v166
	ds_read_b32 v139, v139
	ds_read_b32 v166, v168
	ds_read_b32 v168, v167
	ds_read_b32 v167, v170
	ds_read_b32 v169, v169
	v_max_i32_e32 v170, 0xffffff78, v180
	v_max_i32_e32 v171, 0xffffff58, v180
	v_max_i32_e32 v173, 0xffffff57, v180
	v_max_i32_e32 v175, 0xffffff56, v180
	v_lshl_add_u32 v178, v172, 2, s80
	v_max_i32_e32 v172, 0xffffff75, v180
	v_max_i32_e32 v179, 0xffffff55, v180
	v_add_u32_e32 v170, 0x88, v170
	v_add_u32_e32 v171, 0xa8, v171
	v_add_u32_e32 v173, 0xa9, v173
	v_add_u32_e32 v175, 0xaa, v175
	v_add_u32_e32 v172, 0x8b, v172
	v_add_u32_e32 v179, 0xab, v179
	v_max_i32_e32 v184, 0xffffff53, v180
	v_max_i32_e32 v185, 0xffffff52, v180
	v_min_u32_e32 v170, 0x100, v170
	v_min_u32_e32 v171, 0x100, v171
	v_min_u32_e32 v173, 0x100, v173
	v_min_u32_e32 v175, 0x100, v175
	v_min_u32_e32 v172, 0x100, v172
	v_min_u32_e32 v179, 0x100, v179
	v_add_u32_e32 v184, 0xad, v184
	v_add_u32_e32 v185, 0xae, v185
	v_lshl_add_u32 v170, v170, 2, s80
	v_lshl_add_u32 v171, v171, 2, s80
	v_lshl_add_u32 v173, v173, 2, s80
	v_lshl_add_u32 v175, v175, 2, s80
	v_lshl_add_u32 v181, v172, 2, s80
	v_lshl_add_u32 v179, v179, 2, s80
	v_min_u32_e32 v184, 0x100, v184
	v_min_u32_e32 v185, 0x100, v185
	ds_read_b32 v170, v170
	ds_read_b32 v172, v171
	ds_read_b32 v171, v174
	ds_read_b32 v173, v173
	ds_read_b32 v174, v178
	ds_read_b32 v178, v175
	ds_read_b32 v175, v181
	ds_read_b32 v179, v179
	v_max_i32_e32 v181, 0xffffff74, v180
	v_max_i32_e32 v182, 0xffffff54, v180
	v_max_i32_e32 v183, 0xffffff73, v180
	v_lshl_add_u32 v188, v184, 2, s80
	v_max_i32_e32 v184, 0xffffff72, v180
	v_lshl_add_u32 v186, v185, 2, s80
	v_max_i32_e32 v185, 0xffffff71, v180
	v_max_i32_e32 v180, 0xffffff51, v180
	v_add_u32_e32 v181, 0x8c, v181
	v_add_u32_e32 v182, 0xac, v182
	v_add_u32_e32 v183, 0x8d, v183
	v_add_u32_e32 v184, 0x8e, v184
	v_add_u32_e32 v185, 0x8f, v185
	v_add_u32_e32 v180, 0xaf, v180
	v_min_u32_e32 v181, 0x100, v181
	v_min_u32_e32 v182, 0x100, v182
	v_min_u32_e32 v183, 0x100, v183
	v_min_u32_e32 v184, 0x100, v184
	v_min_u32_e32 v185, 0x100, v185
	v_min_u32_e32 v180, 0x100, v180
	v_lshl_add_u32 v181, v181, 2, s80
	v_lshl_add_u32 v182, v182, 2, s80
	v_lshl_add_u32 v183, v183, 2, s80
	v_lshl_add_u32 v184, v184, 2, s80
	v_lshl_add_u32 v185, v185, 2, s80
	v_lshl_add_u32 v187, v180, 2, s80
	ds_read_b32 v180, v181
	ds_read_b32 v182, v182
	ds_read_b32 v184, v184
	ds_read_b32 v185, v185
	ds_read_b32 v181, v183
	ds_read_b32 v187, v187
	ds_read_b32 v186, v186
	ds_read_b32 v183, v188
	s_waitcnt lgkmcnt(0)
	v_pk_add_f32 v[110:111], v[110:111], v[184:185]
	v_pk_add_f32 v[108:109], v[108:109], v[180:181]
	v_pk_add_f32 v[106:107], v[106:107], v[174:175]
	v_pk_add_f32 v[104:105], v[104:105], v[170:171]
	v_pk_add_f32 v[102:103], v[102:103], v[166:167]
	v_pk_add_f32 v[100:101], v[100:101], v[136:137]
	v_pk_add_f32 v[98:99], v[98:99], v[132:133]
	v_pk_add_f32 v[96:97], v[96:97], v[128:129]
	v_pk_add_f32 v[94:95], v[94:95], v[186:187]
	v_pk_add_f32 v[92:93], v[92:93], v[182:183]
	v_pk_add_f32 v[90:91], v[90:91], v[178:179]
	v_pk_add_f32 v[88:89], v[88:89], v[172:173]
	v_pk_add_f32 v[86:87], v[86:87], v[168:169]
	v_pk_add_f32 v[84:85], v[84:85], v[138:139]
	v_pk_add_f32 v[82:83], v[82:83], v[134:135]
	v_pk_add_f32 v[80:81], v[80:81], v[130:131]

.Lattn_negm_keep_1:
	s_addk_i32 s51, 0xffa1
	s_cmp_lt_u32 s51, 0xfffffea3
	s_nop 0
	s_waitcnt lgkmcnt(7)
	v_mfma_f32_32x32x16_bf16 v[96:111], v[80:83], v[112:115], v[64:79]
	s_waitcnt lgkmcnt(5)
	v_mfma_f32_32x32x16_bf16 v[80:95], v[132:135], v[112:115], v[64:79]
	v_mfma_f32_32x32x16_bf16 v[96:111], v[128:131], v[116:119], v[96:111]
	s_waitcnt lgkmcnt(4)
	v_mfma_f32_32x32x16_bf16 v[80:95], v[136:139], v[116:119], v[80:95]
	s_waitcnt lgkmcnt(3)
	v_mfma_f32_32x32x16_bf16 v[96:111], v[140:143], v[120:123], v[96:111]
	s_waitcnt lgkmcnt(1)
	v_mfma_f32_32x32x16_bf16 v[80:95], v[172:175], v[120:123], v[80:95]
	v_mfma_f32_32x32x16_bf16 v[96:111], v[168:171], v[124:127], v[96:111]
	s_waitcnt lgkmcnt(0)
	v_mfma_f32_32x32x16_bf16 v[80:95], v[178:181], v[124:127], v[80:95]
	s_cbranch_scc1 .LBB0_641
	v_add_u32_e32 v178, s20, v166
	v_max_i32_e32 v130, 0xffffff7f, v178
	v_add_u32_e32 v130, 0x81, v130
	s_add_i32 s51, 0, 0x20000
	v_min_u32_e32 v130, 0x100, v130
	v_lshl_add_u32 v132, v130, 2, s51
	v_max_i32_e32 v130, 0xffffff7e, v178
	v_add_u32_e32 v130, 0x82, v130
	v_max_i32_e32 v138, 0xffffff7b, v178
	v_min_u32_e32 v130, 0x100, v130
	v_add_u32_e32 v138, 0x85, v138
	v_max_i32_e32 v128, 0xffffff80, v178
	v_max_i32_e32 v129, 0xffffff60, v178
	v_max_i32_e32 v131, 0xffffff5f, v178
	v_max_i32_e32 v133, 0xffffff5e, v178
	v_lshl_add_u32 v134, v130, 2, s51
	v_max_i32_e32 v130, 0xffffff7d, v178
	v_max_i32_e32 v135, 0xffffff5d, v178
	v_min_u32_e32 v138, 0x100, v138
	v_add_u32_e32 v128, 0x80, v128
	v_add_u32_e32 v129, 0xa0, v129
	v_add_u32_e32 v131, 0xa1, v131
	v_add_u32_e32 v133, 0xa2, v133
	v_add_u32_e32 v130, 0x83, v130
	v_add_u32_e32 v135, 0xa3, v135
	v_lshl_add_u32 v140, v138, 2, s51
	v_max_i32_e32 v138, 0xffffff7a, v178
	v_min_u32_e32 v128, 0x100, v128
	v_min_u32_e32 v129, 0x100, v129
	v_min_u32_e32 v131, 0x100, v131
	v_min_u32_e32 v133, 0x100, v133
	v_min_u32_e32 v130, 0x100, v130
	v_min_u32_e32 v135, 0x100, v135
	v_add_u32_e32 v138, 0x86, v138
	v_max_i32_e32 v170, 0xffffff77, v178
	v_lshl_add_u32 v128, v128, 2, s51
	v_lshl_add_u32 v129, v129, 2, s51
	v_lshl_add_u32 v131, v131, 2, s51
	v_lshl_add_u32 v133, v133, 2, s51
	v_lshl_add_u32 v136, v130, 2, s51
	v_lshl_add_u32 v135, v135, 2, s51
	v_min_u32_e32 v138, 0x100, v138
	v_add_u32_e32 v170, 0x89, v170
	ds_read_b32 v128, v128
	ds_read_b32 v130, v129
	ds_read_b32 v129, v132
	ds_read_b32 v131, v131
	ds_read_b32 v132, v134
	ds_read_b32 v134, v133
	ds_read_b32 v133, v136
	ds_read_b32 v135, v135
	v_max_i32_e32 v136, 0xffffff7c, v178
	v_max_i32_e32 v137, 0xffffff5c, v178
	v_max_i32_e32 v139, 0xffffff5b, v178
	v_max_i32_e32 v141, 0xffffff5a, v178
	v_lshl_add_u32 v142, v138, 2, s51
	v_max_i32_e32 v138, 0xffffff79, v178
	v_max_i32_e32 v143, 0xffffff59, v178
	v_min_u32_e32 v170, 0x100, v170
	v_add_u32_e32 v136, 0x84, v136
	v_add_u32_e32 v137, 0xa4, v137
	v_add_u32_e32 v139, 0xa5, v139
	v_add_u32_e32 v141, 0xa6, v141
	v_add_u32_e32 v138, 0x87, v138
	v_add_u32_e32 v143, 0xa7, v143
	v_lshl_add_u32 v172, v170, 2, s51
	v_max_i32_e32 v170, 0xffffff76, v178
	v_min_u32_e32 v136, 0x100, v136
	v_min_u32_e32 v137, 0x100, v137
	v_min_u32_e32 v139, 0x100, v139
	v_min_u32_e32 v141, 0x100, v141
	v_min_u32_e32 v138, 0x100, v138
	v_min_u32_e32 v143, 0x100, v143
	v_add_u32_e32 v170, 0x8a, v170
	v_lshl_add_u32 v136, v136, 2, s51
	v_lshl_add_u32 v137, v137, 2, s51
	v_lshl_add_u32 v139, v139, 2, s51
	v_lshl_add_u32 v141, v141, 2, s51
	v_lshl_add_u32 v168, v138, 2, s51
	v_lshl_add_u32 v143, v143, 2, s51
	v_min_u32_e32 v170, 0x100, v170
	ds_read_b32 v136, v136
	ds_read_b32 v138, v137
	ds_read_b32 v137, v140
	ds_read_b32 v139, v139
	ds_read_b32 v140, v142
	ds_read_b32 v142, v141
	ds_read_b32 v141, v168
	ds_read_b32 v143, v143
	v_max_i32_e32 v168, 0xffffff78, v178
	v_max_i32_e32 v169, 0xffffff58, v178
	v_max_i32_e32 v171, 0xffffff57, v178
	v_max_i32_e32 v173, 0xffffff56, v178
	v_lshl_add_u32 v174, v170, 2, s51
	v_max_i32_e32 v170, 0xffffff75, v178
	v_max_i32_e32 v175, 0xffffff55, v178
	v_add_u32_e32 v168, 0x88, v168
	v_add_u32_e32 v169, 0xa8, v169
	v_add_u32_e32 v171, 0xa9, v171
	v_add_u32_e32 v173, 0xaa, v173
	v_add_u32_e32 v170, 0x8b, v170
	v_add_u32_e32 v175, 0xab, v175
	v_max_i32_e32 v182, 0xffffff53, v178
	v_max_i32_e32 v183, 0xffffff52, v178
	v_min_u32_e32 v168, 0x100, v168
	v_min_u32_e32 v169, 0x100, v169
	v_min_u32_e32 v171, 0x100, v171
	v_min_u32_e32 v173, 0x100, v173
	v_min_u32_e32 v170, 0x100, v170
	v_min_u32_e32 v175, 0x100, v175
	v_add_u32_e32 v182, 0xad, v182
	v_add_u32_e32 v183, 0xae, v183
	v_lshl_add_u32 v168, v168, 2, s51
	v_lshl_add_u32 v169, v169, 2, s51
	v_lshl_add_u32 v171, v171, 2, s51
	v_lshl_add_u32 v173, v173, 2, s51
	v_lshl_add_u32 v179, v170, 2, s51
	v_lshl_add_u32 v175, v175, 2, s51
	v_min_u32_e32 v182, 0x100, v182
	v_min_u32_e32 v183, 0x100, v183
	ds_read_b32 v168, v168
	ds_read_b32 v170, v169
	ds_read_b32 v169, v172
	ds_read_b32 v171, v171
	ds_read_b32 v172, v174
	ds_read_b32 v174, v173
	ds_read_b32 v173, v179
	ds_read_b32 v175, v175
	v_max_i32_e32 v179, 0xffffff74, v178
	v_max_i32_e32 v180, 0xffffff54, v178
	v_max_i32_e32 v181, 0xffffff73, v178
	v_lshl_add_u32 v186, v182, 2, s51
	v_max_i32_e32 v182, 0xffffff72, v178
	v_lshl_add_u32 v184, v183, 2, s51
	v_max_i32_e32 v183, 0xffffff71, v178
	v_max_i32_e32 v178, 0xffffff51, v178
	v_add_u32_e32 v179, 0x8c, v179
	v_add_u32_e32 v180, 0xac, v180
	v_add_u32_e32 v181, 0x8d, v181
	v_add_u32_e32 v182, 0x8e, v182
	v_add_u32_e32 v183, 0x8f, v183
	v_add_u32_e32 v178, 0xaf, v178
	v_min_u32_e32 v179, 0x100, v179
	v_min_u32_e32 v180, 0x100, v180
	v_min_u32_e32 v181, 0x100, v181
	v_min_u32_e32 v182, 0x100, v182
	v_min_u32_e32 v183, 0x100, v183
	v_min_u32_e32 v178, 0x100, v178
	v_lshl_add_u32 v179, v179, 2, s51
	v_lshl_add_u32 v180, v180, 2, s51
	v_lshl_add_u32 v181, v181, 2, s51
	v_lshl_add_u32 v182, v182, 2, s51
	v_lshl_add_u32 v183, v183, 2, s51
	v_lshl_add_u32 v185, v178, 2, s51
	ds_read_b32 v178, v179
	ds_read_b32 v180, v180
	ds_read_b32 v182, v182
	ds_read_b32 v183, v183
	ds_read_b32 v179, v181
	ds_read_b32 v185, v185
	ds_read_b32 v184, v184
	ds_read_b32 v181, v186
	s_waitcnt lgkmcnt(0)
	v_pk_add_f32 v[110:111], v[110:111], v[182:183]
	v_pk_add_f32 v[108:109], v[108:109], v[178:179]
	v_pk_add_f32 v[106:107], v[106:107], v[172:173]
	v_pk_add_f32 v[104:105], v[104:105], v[168:169]
	v_pk_add_f32 v[102:103], v[102:103], v[140:141]
	v_pk_add_f32 v[100:101], v[100:101], v[136:137]
	v_pk_add_f32 v[98:99], v[98:99], v[132:133]
	v_pk_add_f32 v[96:97], v[96:97], v[128:129]
	v_pk_add_f32 v[94:95], v[94:95], v[184:185]
	v_pk_add_f32 v[92:93], v[92:93], v[180:181]
	v_pk_add_f32 v[90:91], v[90:91], v[174:175]
	v_pk_add_f32 v[88:89], v[88:89], v[170:171]
	v_pk_add_f32 v[86:87], v[86:87], v[142:143]
	v_pk_add_f32 v[84:85], v[84:85], v[138:139]
	v_pk_add_f32 v[82:83], v[82:83], v[134:135]
	v_pk_add_f32 v[80:81], v[80:81], v[130:131]

.LBB0_643:
	v_add_u32_e32 v128, s50, v164
	s_waitcnt lgkmcnt(0)
	s_barrier
	v_add_u32_e32 v168, v128, v165
	ds_read_b128 v[140:143], v168 offset:18432
	ds_read_b128 v[132:135], v168 offset:18448
	ds_read_b128 v[136:139], v168 offset:23040
	ds_read_b128 v[128:131], v168 offset:23056
	ds_read_b128 v[178:181], v168 offset:27648
	ds_read_b128 v[182:185], v168 offset:27664
	ds_read_b128 v[186:189], v168 offset:32256
	ds_read_b128 v[190:193], v168 offset:32272
	v_exp_f32_e32 v96, v96
	v_exp_f32_e32 v97, v97
	v_exp_f32_e32 v98, v98
	v_exp_f32_e32 v99, v99
	v_exp_f32_e32 v100, v100
	v_exp_f32_e32 v101, v101
	v_exp_f32_e32 v102, v102
	v_exp_f32_e32 v103, v103
	v_exp_f32_e32 v104, v104
	v_exp_f32_e32 v105, v105
	v_exp_f32_e32 v106, v106
	v_exp_f32_e32 v107, v107
	v_exp_f32_e32 v108, v108
	v_exp_f32_e32 v109, v109
	v_exp_f32_e32 v110, v110
	v_exp_f32_e32 v111, v111
	v_cvt_pk_bf16_f32 v170, v96, v97
	v_cvt_pk_bf16_f32 v171, v98, v99
	v_cvt_pk_bf16_f32 v172, v100, v101
	v_cvt_pk_bf16_f32 v173, v102, v103
	v_cvt_pk_bf16_f32 v194, v104, v105
	v_cvt_pk_bf16_f32 v195, v106, v107
	v_cvt_pk_bf16_f32 v196, v108, v109
	v_cvt_pk_bf16_f32 v197, v110, v111
	s_waitcnt lgkmcnt(7)
	v_mfma_f32_32x32x16_bf16 v[48:63], v[140:143], v[170:173], v[48:63]
	v_exp_f32_e32 v80, v80
	v_exp_f32_e32 v81, v81
	v_exp_f32_e32 v82, v82
	v_exp_f32_e32 v83, v83
	s_waitcnt lgkmcnt(5)
	v_mfma_f32_32x32x16_bf16 v[0:15], v[136:139], v[170:173], v[0:15]
	v_mfma_f32_32x32x16_bf16 v[48:63], v[132:135], v[194:197], v[48:63]
	v_exp_f32_e32 v84, v84
	v_exp_f32_e32 v85, v85
	v_exp_f32_e32 v86, v86
	v_exp_f32_e32 v87, v87
	s_waitcnt lgkmcnt(4)
	v_mfma_f32_32x32x16_bf16 v[0:15], v[128:131], v[194:197], v[0:15]
	ds_read_b128 v[128:131], v168 offset:18496
	ds_read_b128 v[132:135], v168 offset:18512
	ds_read_b128 v[136:139], v168 offset:23104
	ds_read_b128 v[140:143], v168 offset:23120
	s_waitcnt lgkmcnt(7)
	v_mfma_f32_32x32x16_bf16 v[32:47], v[178:181], v[170:173], v[32:47]
	v_exp_f32_e32 v88, v88
	v_exp_f32_e32 v89, v89
	v_exp_f32_e32 v90, v90
	v_exp_f32_e32 v91, v91
	s_waitcnt lgkmcnt(5)
	v_mfma_f32_32x32x16_bf16 v[16:31], v[186:189], v[170:173], v[16:31]
	v_mfma_f32_32x32x16_bf16 v[32:47], v[182:185], v[194:197], v[32:47]
	v_exp_f32_e32 v92, v92
	v_exp_f32_e32 v93, v93
	v_exp_f32_e32 v94, v94
	v_exp_f32_e32 v95, v95
	v_cvt_pk_bf16_f32 v170, v80, v81
	v_cvt_pk_bf16_f32 v171, v82, v83
	v_cvt_pk_bf16_f32 v172, v84, v85
	s_waitcnt lgkmcnt(4)
	v_mfma_f32_32x32x16_bf16 v[16:31], v[190:193], v[194:197], v[16:31]
	v_cvt_pk_bf16_f32 v173, v86, v87
	v_cvt_pk_bf16_f32 v178, v88, v89
	v_cvt_pk_bf16_f32 v179, v90, v91
	v_cvt_pk_bf16_f32 v180, v92, v93
	v_cvt_pk_bf16_f32 v181, v94, v95
	ds_read_b128 v[182:185], v168 offset:27712
	ds_read_b128 v[186:189], v168 offset:27728
	ds_read_b128 v[190:193], v168 offset:32320
	ds_read_b128 v[194:197], v168 offset:32336
	s_cmp_gt_u32 s33, 61
	s_cselect_b64 s[50:51], -1, 0
	s_and_b64 vcc, exec, s[50:51]
	s_cbranch_vccnz .LBB0_645
	s_mul_i32 s63, s45, 0x9000
	s_or_b32 s64, s63, s35
	s_and_b64 s[60:61], s[54:55], exec
	s_cselect_b32 m0, s64, s82
	s_nop 0
	global_load_lds_dwordx4 v[240:241], off
	s_and_b64 s[60:61], s[38:39], exec
	s_cselect_b32 s60, s63, 0x12000
	s_add_i32 m0, s2, s60
	v_lshl_add_u64 v[240:241], v[240:241], 0, v[200:201]
	global_load_lds_dwordx4 v[242:243], off
	s_add_i32 s64, s63, s21
	s_and_b64 s[60:61], s[40:41], exec
	s_cselect_b32 m0, s64, s8
	v_lshl_add_u64 v[242:243], v[242:243], 0, v[202:203]
	global_load_lds_dwordx4 v[244:245], off
	s_and_b64 s[60:61], s[42:43], exec
	s_cselect_b32 s60, s63, 0x12000
	s_add_i32 m0, s26, s60
	v_lshl_add_u64 v[244:245], v[244:245], 0, v[204:205]
	global_load_lds_dwordx4 v[246:247], off
	s_add_i32 s63, s63, s3
	s_and_b64 s[60:61], s[46:47], exec
	s_cselect_b32 m0, s63, s9
	v_lshl_add_u64 v[246:247], v[246:247], 0, v[206:207]
	global_load_lds_dwordx4 v[248:249], off
	v_lshl_add_u64 v[248:249], v[248:249], 0, v[208:209]
.LBB0_645:
	s_waitcnt lgkmcnt(7)
	v_mfma_f32_32x32x16_bf16 v[48:63], v[128:131], v[170:173], v[48:63]
	v_add_f32_e32 v96, v97, v96
	v_add_f32_e32 v96, v98, v96
	v_add_f32_e32 v80, v81, v80
	v_add_f32_e32 v96, v99, v96
	s_waitcnt lgkmcnt(5)
	v_mfma_f32_32x32x16_bf16 v[0:15], v[136:139], v[170:173], v[0:15]
	v_add_f32_e32 v80, v82, v80
	v_add_f32_e32 v96, v100, v96
	v_add_f32_e32 v80, v83, v80
	v_add_f32_e32 v96, v101, v96
	v_mfma_f32_32x32x16_bf16 v[48:63], v[132:135], v[178:181], v[48:63]
	v_add_f32_e32 v80, v84, v80
	v_add_f32_e32 v96, v102, v96
	v_add_f32_e32 v80, v85, v80
	v_add_f32_e32 v96, v103, v96
	s_waitcnt lgkmcnt(4)
	v_mfma_f32_32x32x16_bf16 v[0:15], v[140:143], v[178:181], v[0:15]
	v_add_f32_e32 v80, v86, v80
	v_add_f32_e32 v96, v104, v96
	v_add_f32_e32 v80, v87, v80
	v_add_f32_e32 v96, v105, v96
	s_waitcnt lgkmcnt(3)
	v_mfma_f32_32x32x16_bf16 v[32:47], v[182:185], v[170:173], v[32:47]
	v_add_f32_e32 v80, v88, v80
	v_add_f32_e32 v96, v106, v96
	v_add_f32_e32 v80, v89, v80
	v_add_f32_e32 v96, v107, v96
	s_waitcnt lgkmcnt(1)
	v_mfma_f32_32x32x16_bf16 v[16:31], v[190:193], v[170:173], v[16:31]
	v_add_f32_e32 v80, v90, v80
	v_add_f32_e32 v96, v108, v96
	v_add_f32_e32 v80, v91, v80
	v_add_f32_e32 v96, v109, v96
	v_mfma_f32_32x32x16_bf16 v[32:47], v[186:189], v[178:181], v[32:47]
	v_add_f32_e32 v80, v92, v80
	v_add_f32_e32 v96, v110, v96
	v_add_f32_e32 v80, v93, v80
	v_add_f32_e32 v96, v111, v96
	s_waitcnt lgkmcnt(0)
	v_mfma_f32_32x32x16_bf16 v[16:31], v[194:197], v[178:181], v[16:31]
	v_add_f32_e32 v80, v94, v80
	v_add_f32_e32 v96, v157, v96
	v_add_f32_e32 v80, v95, v80
	v_add_f32_e32 v157, v96, v80
	s_mov_b64 s[60:61], -1
	s_and_b64 vcc, exec, s[50:51]
	s_cbranch_vccz .LBB0_647
	s_waitcnt vmcnt(0) lgkmcnt(0)
	s_barrier
	s_mov_b64 s[60:61], 0

.LBB0_683:
	v_add3_u32 v165, s57, v143, v163
	ds_read_b128 v[190:193], v165 offset:18432
	ds_read_b128 v[194:197], v165 offset:18448
	ds_read_b128 v[128:131], v165 offset:23040
	ds_read_b128 v[132:135], v165 offset:23056
	ds_read_b128 v[136:139], v165 offset:27648
	ds_read_b128 v[166:169], v165 offset:27664
	ds_read_b128 v[170:173], v165 offset:32256
	ds_read_b128 v[178:181], v165 offset:32272
	v_exp_f32_e32 v96, v96
	v_exp_f32_e32 v97, v97
	v_exp_f32_e32 v98, v98
	v_exp_f32_e32 v99, v99
	v_exp_f32_e32 v100, v100
	v_add_f32_e32 v198, v97, v96
	v_exp_f32_e32 v101, v101
	v_add_f32_e32 v198, v98, v198
	v_exp_f32_e32 v102, v102
	v_add_f32_e32 v198, v99, v198
	v_exp_f32_e32 v103, v103
	v_add_f32_e32 v198, v100, v198
	v_exp_f32_e32 v104, v104
	v_add_f32_e32 v198, v101, v198
	v_exp_f32_e32 v105, v105
	v_add_f32_e32 v198, v102, v198
	v_exp_f32_e32 v106, v106
	v_add_f32_e32 v198, v103, v198
	v_exp_f32_e32 v107, v107
	v_add_f32_e32 v198, v104, v198
	v_exp_f32_e32 v108, v108
	v_add_f32_e32 v198, v105, v198
	v_exp_f32_e32 v109, v109
	v_add_f32_e32 v198, v106, v198
	v_exp_f32_e32 v110, v110
	v_add_f32_e32 v198, v107, v198
	v_exp_f32_e32 v111, v111
	v_add_f32_e32 v198, v108, v198
	v_add_f32_e32 v198, v109, v198
	v_add_f32_e32 v198, v110, v198
	v_add_f32_e32 v198, v111, v198
	v_add_f32_e32 v157, v157, v198
	v_cvt_pk_bf16_f32 v96, v96, v97
	v_cvt_pk_bf16_f32 v97, v98, v99
	v_cvt_pk_bf16_f32 v98, v100, v101
	v_cvt_pk_bf16_f32 v99, v102, v103
	v_cvt_pk_bf16_f32 v100, v104, v105
	v_cvt_pk_bf16_f32 v101, v106, v107
	v_cvt_pk_bf16_f32 v102, v108, v109
	v_cvt_pk_bf16_f32 v103, v110, v111
	s_waitcnt lgkmcnt(7)
	v_mfma_f32_32x32x16_bf16 v[48:63], v[190:193], v[96:99], v[48:63]
	v_exp_f32_e32 v174, v80
	v_exp_f32_e32 v175, v81
	v_exp_f32_e32 v182, v82
	v_exp_f32_e32 v183, v83
	v_add_f32_e32 v80, v175, v174
	v_add_f32_e32 v80, v182, v80
	s_waitcnt lgkmcnt(5)
	v_mfma_f32_32x32x16_bf16 v[0:15], v[128:131], v[96:99], v[0:15]
	v_add_f32_e32 v80, v183, v80
	v_mfma_f32_32x32x16_bf16 v[48:63], v[194:197], v[100:103], v[48:63]
	v_exp_f32_e32 v128, v84
	v_exp_f32_e32 v129, v85
	v_exp_f32_e32 v130, v86
	v_exp_f32_e32 v131, v87
	v_add_f32_e32 v80, v128, v80
	v_add_f32_e32 v80, v129, v80
	v_add_f32_e32 v80, v130, v80
	s_waitcnt lgkmcnt(4)
	v_mfma_f32_32x32x16_bf16 v[0:15], v[132:135], v[100:103], v[0:15]
	v_add_f32_e32 v184, v131, v80
	ds_read_b128 v[80:83], v165 offset:18496
	ds_read_b128 v[84:87], v165 offset:18512
	ds_read_b128 v[104:107], v165 offset:23104
	ds_read_b128 v[108:111], v165 offset:23120
	s_waitcnt lgkmcnt(7)
	v_mfma_f32_32x32x16_bf16 v[32:47], v[136:139], v[96:99], v[32:47]
	v_exp_f32_e32 v132, v88
	v_exp_f32_e32 v133, v89
	v_exp_f32_e32 v134, v90
	v_exp_f32_e32 v135, v91
	v_add_f32_e32 v88, v132, v184
	v_add_f32_e32 v88, v133, v88
	v_add_f32_e32 v88, v134, v88
	s_waitcnt lgkmcnt(5)
	v_mfma_f32_32x32x16_bf16 v[16:31], v[170:173], v[96:99], v[16:31]
	v_add_f32_e32 v88, v135, v88
	v_exp_f32_e32 v96, v92
	v_mfma_f32_32x32x16_bf16 v[32:47], v[166:169], v[100:103], v[32:47]
	v_exp_f32_e32 v97, v93
	v_exp_f32_e32 v98, v94
	v_exp_f32_e32 v95, v95
	v_add_f32_e32 v88, v96, v88
	v_add_f32_e32 v88, v97, v88
	v_add_f32_e32 v88, v98, v88
	v_add_f32_e32 v88, v95, v88
	s_waitcnt lgkmcnt(4)
	v_mfma_f32_32x32x16_bf16 v[16:31], v[178:181], v[100:103], v[16:31]
	v_add_f32_e32 v157, v157, v88
	v_cvt_pk_bf16_f32 v88, v174, v175
	v_cvt_pk_bf16_f32 v89, v182, v183
	v_cvt_pk_bf16_f32 v90, v128, v129
	v_cvt_pk_bf16_f32 v91, v130, v131
	v_cvt_pk_bf16_f32 v92, v132, v133
	v_cvt_pk_bf16_f32 v93, v134, v135
	v_cvt_pk_bf16_f32 v94, v96, v97
	v_cvt_pk_bf16_f32 v95, v98, v95
	ds_read_b128 v[96:99], v165 offset:27712
	ds_read_b128 v[100:103], v165 offset:27728
	ds_read_b128 v[128:131], v165 offset:32320
	ds_read_b128 v[132:135], v165 offset:32336
	s_waitcnt lgkmcnt(7)
	v_mfma_f32_32x32x16_bf16 v[48:63], v[80:83], v[88:91], v[48:63]
	s_waitcnt lgkmcnt(5)
	v_mfma_f32_32x32x16_bf16 v[0:15], v[104:107], v[88:91], v[0:15]
	v_mfma_f32_32x32x16_bf16 v[48:63], v[84:87], v[92:95], v[48:63]
	s_waitcnt lgkmcnt(4)
	v_mfma_f32_32x32x16_bf16 v[0:15], v[108:111], v[92:95], v[0:15]
	s_waitcnt lgkmcnt(3)
	v_mfma_f32_32x32x16_bf16 v[32:47], v[96:99], v[88:91], v[32:47]
	s_waitcnt lgkmcnt(1)
	v_mfma_f32_32x32x16_bf16 v[16:31], v[128:131], v[88:91], v[16:31]
	v_mfma_f32_32x32x16_bf16 v[32:47], v[100:103], v[92:95], v[32:47]
	s_waitcnt lgkmcnt(0)
	v_mfma_f32_32x32x16_bf16 v[16:31], v[132:135], v[92:95], v[16:31]
	s_add_i32 s4, s9, 0x9000
	s_cmp_lg_u32 s9, 0x12000
	s_cselect_b32 s9, s4, 0
	s_add_i32 s4, s56, 1
	s_cmp_lg_u32 s56, 2
	s_cselect_b32 s56, s4, 0
	s_add_i32 s8, s8, 1
	s_add_u32 s76, s76, 0x80
	s_addc_u32 s77, s77, 0
	s_add_u32 s10, s10, 0x60000
	s_waitcnt lgkmcnt(0)
	s_barrier
	s_addc_u32 s11, s11, 0
	s_add_i32 s58, s58, 64
	s_cmpk_lg_i32 s58, 0x7c0
	s_cbranch_scc0 .LBB0_694
.LBB0_684:
	s_add_i32 s57, s9, 0
	s_add_i32 s4, s57, s94
	v_add_u32_e32 v80, s4, v162
	v_add_u32_e32 v84, v80, v146
	ds_read_b128 v[80:83], v84
	ds_read_b128 v[128:131], v84 offset:32
	ds_read_b128 v[136:139], v84 offset:4608
	ds_read_b128 v[132:135], v84 offset:4640
	ds_read_b128 v[166:169], v84 offset:64
	ds_read_b128 v[170:173], v84 offset:96
	ds_read_b128 v[178:181], v84 offset:4672
	ds_read_b128 v[182:185], v84 offset:4704
	s_cmp_gt_u32 s8, 29
	s_cselect_b64 s[78:79], -1, 0
	s_and_b64 vcc, exec, s[78:79]
	s_cbranch_vccnz .LBB0_686
	s_mul_i32 vcc_lo, s56, 0x9000
	s_add_i32 vcc_hi, vcc_lo, s35
	s_and_b64 s[80:81], s[54:55], exec
	s_cselect_b32 m0, vcc_hi, s82
	s_nop 0
	global_load_lds_dwordx4 v[240:241], off
	s_add_i32 vcc_hi, vcc_lo, s33
	s_and_b64 s[80:81], s[64:65], exec
	s_cselect_b32 m0, vcc_hi, s2
	v_lshl_add_u64 v[240:241], v[240:241], 0, v[200:201]
	global_load_lds_dwordx4 v[242:243], off
	s_add_i32 vcc_hi, vcc_lo, s93
	s_and_b64 s[80:81], s[42:43], exec
	s_cselect_b32 m0, vcc_hi, s92
	v_lshl_add_u64 v[242:243], v[242:243], 0, v[202:203]
	global_load_lds_dwordx4 v[244:245], off
	s_add_i32 vcc_hi, vcc_lo, s45
	s_and_b64 s[80:81], s[24:25], exec
	s_cselect_b32 m0, vcc_hi, s97
	v_lshl_add_u64 v[244:245], v[244:245], 0, v[204:205]
	global_load_lds_dwordx4 v[246:247], off
	s_add_i32 vcc_hi, vcc_lo, s59
	s_and_b64 s[80:81], s[70:71], exec
	s_cselect_b32 m0, vcc_hi, s86
	v_lshl_add_u64 v[246:247], v[246:247], 0, v[206:207]
	global_load_lds_dwordx4 v[248:249], off
	v_lshl_add_u64 v[248:249], v[248:249], 0, v[208:209]
.LBB0_686:
	s_add_i32 s16, s91, s58
	s_add_i32 s4, s16, 64
	s_cmpk_lt_i32 s4, 0xff42
	s_cselect_b32 s5, 1, 0
	s_cmpk_gt_i32 s4, 0x9e
	s_cselect_b32 s4, 2, s5
	s_cmp_eq_u32 s4, s32
	s_cbranch_scc1 .Lattn_negm_keep_2
	s_mov_b32 s32, s4
	s_cmp_eq_u32 s4, 1
	s_cselect_b64 vcc, -1, 0
	s_cmp_eq_u32 s4, 2
	s_cselect_b64 s[4:5], -1, 0
	v_cndmask_b32_e64 v84, 0, v160, s[4:5]
	v_cndmask_b32_e32 v252, v84, v159, vcc
	v_sub_f32_e32 v84, v252, v156
	v_mov_b32_e32 v79, v84
	v_mov_b32_e32 v78, v84
	v_mov_b32_e32 v77, v84
	v_mov_b32_e32 v76, v84
	v_mov_b32_e32 v75, v84
	v_mov_b32_e32 v74, v84
	v_mov_b32_e32 v73, v84
	v_mov_b32_e32 v72, v84
	v_mov_b32_e32 v71, v84
	v_mov_b32_e32 v70, v84
	v_mov_b32_e32 v69, v84
	v_mov_b32_e32 v68, v84
	v_mov_b32_e32 v67, v84
	v_mov_b32_e32 v66, v84
	v_mov_b32_e32 v65, v84
	v_mov_b32_e32 v64, v84
.Lattn_negm_keep_2:
	s_addk_i32 s16, 0xffa1
	s_cmp_lt_u32 s16, 0xfffffea3
	s_nop 0
	s_waitcnt lgkmcnt(7)
	v_mfma_f32_32x32x16_bf16 v[96:111], v[80:83], v[112:115], v[64:79]
	s_waitcnt lgkmcnt(5)
	v_mfma_f32_32x32x16_bf16 v[80:95], v[136:139], v[112:115], v[64:79]
	v_mfma_f32_32x32x16_bf16 v[96:111], v[128:131], v[116:119], v[96:111]
	s_waitcnt lgkmcnt(4)
	v_mfma_f32_32x32x16_bf16 v[80:95], v[132:135], v[116:119], v[80:95]
	s_waitcnt lgkmcnt(3)
	v_mfma_f32_32x32x16_bf16 v[96:111], v[166:169], v[120:123], v[96:111]
	s_waitcnt lgkmcnt(1)
	v_mfma_f32_32x32x16_bf16 v[80:95], v[178:181], v[120:123], v[80:95]
	v_mfma_f32_32x32x16_bf16 v[96:111], v[170:173], v[124:127], v[96:111]
	s_waitcnt lgkmcnt(0)
	v_mfma_f32_32x32x16_bf16 v[80:95], v[182:185], v[124:127], v[80:95]
	s_cbranch_scc1 .LBB0_688
	v_add_u32_e32 v180, s58, v164
	v_max_i32_e32 v130, 0xffffff7f, v180
	v_add_u32_e32 v130, 0x81, v130
	s_add_i32 s80, 0, 0x20000
	v_min_u32_e32 v130, 0x100, v130
	v_lshl_add_u32 v132, v130, 2, s80
	v_max_i32_e32 v130, 0xffffff7e, v180
	v_add_u32_e32 v130, 0x82, v130
	v_max_i32_e32 v138, 0xffffff7b, v180
	v_min_u32_e32 v130, 0x100, v130
	v_add_u32_e32 v138, 0x85, v138
	v_max_i32_e32 v128, 0xffffff80, v180
	v_max_i32_e32 v129, 0xffffff60, v180
	v_max_i32_e32 v131, 0xffffff5f, v180
	v_max_i32_e32 v133, 0xffffff5e, v180
	v_lshl_add_u32 v134, v130, 2, s80
	v_max_i32_e32 v130, 0xffffff7d, v180
	v_max_i32_e32 v135, 0xffffff5d, v180
	v_min_u32_e32 v138, 0x100, v138
	v_add_u32_e32 v128, 0x80, v128
	v_add_u32_e32 v129, 0xa0, v129
	v_add_u32_e32 v131, 0xa1, v131
	v_add_u32_e32 v133, 0xa2, v133
	v_add_u32_e32 v130, 0x83, v130
	v_add_u32_e32 v135, 0xa3, v135
	v_lshl_add_u32 v166, v138, 2, s80
	v_max_i32_e32 v138, 0xffffff7a, v180
	v_min_u32_e32 v128, 0x100, v128
	v_min_u32_e32 v129, 0x100, v129
	v_min_u32_e32 v131, 0x100, v131
	v_min_u32_e32 v133, 0x100, v133
	v_min_u32_e32 v130, 0x100, v130
	v_min_u32_e32 v135, 0x100, v135
	v_add_u32_e32 v138, 0x86, v138
	v_max_i32_e32 v172, 0xffffff77, v180
	v_lshl_add_u32 v128, v128, 2, s80
	v_lshl_add_u32 v129, v129, 2, s80
	v_lshl_add_u32 v131, v131, 2, s80
	v_lshl_add_u32 v133, v133, 2, s80
	v_lshl_add_u32 v136, v130, 2, s80
	v_lshl_add_u32 v135, v135, 2, s80
	v_min_u32_e32 v138, 0x100, v138
	v_add_u32_e32 v172, 0x89, v172
	ds_read_b32 v128, v128
	ds_read_b32 v130, v129
	ds_read_b32 v129, v132
	ds_read_b32 v131, v131
	ds_read_b32 v132, v134
	ds_read_b32 v134, v133
	ds_read_b32 v133, v136
	ds_read_b32 v135, v135
	v_max_i32_e32 v136, 0xffffff7c, v180
	v_max_i32_e32 v137, 0xffffff5c, v180
	v_max_i32_e32 v139, 0xffffff5b, v180
	v_max_i32_e32 v167, 0xffffff5a, v180
	v_lshl_add_u32 v168, v138, 2, s80
	v_max_i32_e32 v138, 0xffffff79, v180
	v_max_i32_e32 v169, 0xffffff59, v180
	v_min_u32_e32 v172, 0x100, v172
	v_add_u32_e32 v136, 0x84, v136
	v_add_u32_e32 v137, 0xa4, v137
	v_add_u32_e32 v139, 0xa5, v139
	v_add_u32_e32 v167, 0xa6, v167
	v_add_u32_e32 v138, 0x87, v138
	v_add_u32_e32 v169, 0xa7, v169
	v_lshl_add_u32 v174, v172, 2, s80
	v_max_i32_e32 v172, 0xffffff76, v180
	v_min_u32_e32 v136, 0x100, v136
	v_min_u32_e32 v137, 0x100, v137
	v_min_u32_e32 v139, 0x100, v139
	v_min_u32_e32 v167, 0x100, v167
	v_min_u32_e32 v138, 0x100, v138
	v_min_u32_e32 v169, 0x100, v169
	v_add_u32_e32 v172, 0x8a, v172
	v_lshl_add_u32 v136, v136, 2, s80
	v_lshl_add_u32 v137, v137, 2, s80
	v_lshl_add_u32 v139, v139, 2, s80
	v_lshl_add_u32 v167, v167, 2, s80
	v_lshl_add_u32 v170, v138, 2, s80
	v_lshl_add_u32 v169, v169, 2, s80
	v_min_u32_e32 v172, 0x100, v172
	ds_read_b32 v136, v136
	ds_read_b32 v138, v137
	ds_read_b32 v137, v166
	ds_read_b32 v139, v139
	ds_read_b32 v166, v168
	ds_read_b32 v168, v167
	ds_read_b32 v167, v170
	ds_read_b32 v169, v169
	v_max_i32_e32 v170, 0xffffff78, v180
	v_max_i32_e32 v171, 0xffffff58, v180
	v_max_i32_e32 v173, 0xffffff57, v180
	v_max_i32_e32 v175, 0xffffff56, v180
	v_lshl_add_u32 v178, v172, 2, s80
	v_max_i32_e32 v172, 0xffffff75, v180
	v_max_i32_e32 v179, 0xffffff55, v180
	v_add_u32_e32 v170, 0x88, v170
	v_add_u32_e32 v171, 0xa8, v171
	v_add_u32_e32 v173, 0xa9, v173
	v_add_u32_e32 v175, 0xaa, v175
	v_add_u32_e32 v172, 0x8b, v172
	v_add_u32_e32 v179, 0xab, v179
	v_max_i32_e32 v184, 0xffffff53, v180
	v_max_i32_e32 v185, 0xffffff52, v180
	v_min_u32_e32 v170, 0x100, v170
	v_min_u32_e32 v171, 0x100, v171
	v_min_u32_e32 v173, 0x100, v173
	v_min_u32_e32 v175, 0x100, v175
	v_min_u32_e32 v172, 0x100, v172
	v_min_u32_e32 v179, 0x100, v179
	v_add_u32_e32 v184, 0xad, v184
	v_add_u32_e32 v185, 0xae, v185
	v_lshl_add_u32 v170, v170, 2, s80
	v_lshl_add_u32 v171, v171, 2, s80
	v_lshl_add_u32 v173, v173, 2, s80
	v_lshl_add_u32 v175, v175, 2, s80
	v_lshl_add_u32 v181, v172, 2, s80
	v_lshl_add_u32 v179, v179, 2, s80
	v_min_u32_e32 v184, 0x100, v184
	v_min_u32_e32 v185, 0x100, v185
	ds_read_b32 v170, v170
	ds_read_b32 v172, v171
	ds_read_b32 v171, v174
	ds_read_b32 v173, v173
	ds_read_b32 v174, v178
	ds_read_b32 v178, v175
	ds_read_b32 v175, v181
	ds_read_b32 v179, v179
	v_max_i32_e32 v181, 0xffffff74, v180
	v_max_i32_e32 v182, 0xffffff54, v180
	v_max_i32_e32 v183, 0xffffff73, v180
	v_lshl_add_u32 v188, v184, 2, s80
	v_max_i32_e32 v184, 0xffffff72, v180
	v_lshl_add_u32 v186, v185, 2, s80
	v_max_i32_e32 v185, 0xffffff71, v180
	v_max_i32_e32 v180, 0xffffff51, v180
	v_add_u32_e32 v181, 0x8c, v181
	v_add_u32_e32 v182, 0xac, v182
	v_add_u32_e32 v183, 0x8d, v183
	v_add_u32_e32 v184, 0x8e, v184
	v_add_u32_e32 v185, 0x8f, v185
	v_add_u32_e32 v180, 0xaf, v180
	v_min_u32_e32 v181, 0x100, v181
	v_min_u32_e32 v182, 0x100, v182
	v_min_u32_e32 v183, 0x100, v183
	v_min_u32_e32 v184, 0x100, v184
	v_min_u32_e32 v185, 0x100, v185
	v_min_u32_e32 v180, 0x100, v180
	v_lshl_add_u32 v181, v181, 2, s80
	v_lshl_add_u32 v182, v182, 2, s80
	v_lshl_add_u32 v183, v183, 2, s80
	v_lshl_add_u32 v184, v184, 2, s80
	v_lshl_add_u32 v185, v185, 2, s80
	v_lshl_add_u32 v187, v180, 2, s80
	ds_read_b32 v180, v181
	ds_read_b32 v182, v182
	ds_read_b32 v184, v184
	ds_read_b32 v185, v185
	ds_read_b32 v181, v183
	ds_read_b32 v187, v187
	ds_read_b32 v186, v186
	ds_read_b32 v183, v188
	s_waitcnt lgkmcnt(0)
	v_pk_add_f32 v[110:111], v[110:111], v[184:185]
	v_pk_add_f32 v[108:109], v[108:109], v[180:181]
	v_pk_add_f32 v[106:107], v[106:107], v[174:175]
	v_pk_add_f32 v[104:105], v[104:105], v[170:171]
	v_pk_add_f32 v[102:103], v[102:103], v[166:167]
	v_pk_add_f32 v[100:101], v[100:101], v[136:137]
	v_pk_add_f32 v[98:99], v[98:99], v[132:133]
	v_pk_add_f32 v[96:97], v[96:97], v[128:129]
	v_pk_add_f32 v[94:95], v[94:95], v[186:187]
	v_pk_add_f32 v[92:93], v[92:93], v[182:183]
	v_pk_add_f32 v[90:91], v[90:91], v[178:179]
	v_pk_add_f32 v[88:89], v[88:89], v[172:173]
	v_pk_add_f32 v[86:87], v[86:87], v[168:169]
	v_pk_add_f32 v[84:85], v[84:85], v[138:139]
	v_pk_add_f32 v[82:83], v[82:83], v[134:135]
	v_pk_add_f32 v[80:81], v[80:81], v[130:131]

.Lattn_negm_keep_3:
	s_addk_i32 s16, 0xffa1
	s_cmp_lt_u32 s16, 0xfffffea3
	s_nop 0
	s_waitcnt lgkmcnt(7)
	v_mfma_f32_32x32x16_bf16 v[96:111], v[80:83], v[112:115], v[64:79]
	s_waitcnt lgkmcnt(5)
	v_mfma_f32_32x32x16_bf16 v[80:95], v[132:135], v[112:115], v[64:79]
	v_mfma_f32_32x32x16_bf16 v[96:111], v[128:131], v[116:119], v[96:111]
	s_waitcnt lgkmcnt(4)
	v_mfma_f32_32x32x16_bf16 v[80:95], v[136:139], v[116:119], v[80:95]
	s_waitcnt lgkmcnt(3)
	v_mfma_f32_32x32x16_bf16 v[96:111], v[140:143], v[120:123], v[96:111]
	s_waitcnt lgkmcnt(1)
	v_mfma_f32_32x32x16_bf16 v[80:95], v[172:175], v[120:123], v[80:95]
	v_mfma_f32_32x32x16_bf16 v[96:111], v[168:171], v[124:127], v[96:111]
	s_waitcnt lgkmcnt(0)
	v_mfma_f32_32x32x16_bf16 v[80:95], v[178:181], v[124:127], v[80:95]
	s_cbranch_scc1 .LBB0_702
	v_add_u32_e32 v178, s20, v166
	v_max_i32_e32 v130, 0xffffff7f, v178
	v_add_u32_e32 v130, 0x81, v130
	s_add_i32 s57, 0, 0x20000
	v_min_u32_e32 v130, 0x100, v130
	v_lshl_add_u32 v132, v130, 2, s57
	v_max_i32_e32 v130, 0xffffff7e, v178
	v_add_u32_e32 v130, 0x82, v130
	v_max_i32_e32 v138, 0xffffff7b, v178
	v_min_u32_e32 v130, 0x100, v130
	v_add_u32_e32 v138, 0x85, v138
	v_max_i32_e32 v128, 0xffffff80, v178
	v_max_i32_e32 v129, 0xffffff60, v178
	v_max_i32_e32 v131, 0xffffff5f, v178
	v_max_i32_e32 v133, 0xffffff5e, v178
	v_lshl_add_u32 v134, v130, 2, s57
	v_max_i32_e32 v130, 0xffffff7d, v178
	v_max_i32_e32 v135, 0xffffff5d, v178
	v_min_u32_e32 v138, 0x100, v138
	v_add_u32_e32 v128, 0x80, v128
	v_add_u32_e32 v129, 0xa0, v129
	v_add_u32_e32 v131, 0xa1, v131
	v_add_u32_e32 v133, 0xa2, v133
	v_add_u32_e32 v130, 0x83, v130
	v_add_u32_e32 v135, 0xa3, v135
	v_lshl_add_u32 v140, v138, 2, s57
	v_max_i32_e32 v138, 0xffffff7a, v178
	v_min_u32_e32 v128, 0x100, v128
	v_min_u32_e32 v129, 0x100, v129
	v_min_u32_e32 v131, 0x100, v131
	v_min_u32_e32 v133, 0x100, v133
	v_min_u32_e32 v130, 0x100, v130
	v_min_u32_e32 v135, 0x100, v135
	v_add_u32_e32 v138, 0x86, v138
	v_max_i32_e32 v170, 0xffffff77, v178
	v_lshl_add_u32 v128, v128, 2, s57
	v_lshl_add_u32 v129, v129, 2, s57
	v_lshl_add_u32 v131, v131, 2, s57
	v_lshl_add_u32 v133, v133, 2, s57
	v_lshl_add_u32 v136, v130, 2, s57
	v_lshl_add_u32 v135, v135, 2, s57
	v_min_u32_e32 v138, 0x100, v138
	v_add_u32_e32 v170, 0x89, v170
	ds_read_b32 v128, v128
	ds_read_b32 v130, v129
	ds_read_b32 v129, v132
	ds_read_b32 v131, v131
	ds_read_b32 v132, v134
	ds_read_b32 v134, v133
	ds_read_b32 v133, v136
	ds_read_b32 v135, v135
	v_max_i32_e32 v136, 0xffffff7c, v178
	v_max_i32_e32 v137, 0xffffff5c, v178
	v_max_i32_e32 v139, 0xffffff5b, v178
	v_max_i32_e32 v141, 0xffffff5a, v178
	v_lshl_add_u32 v142, v138, 2, s57
	v_max_i32_e32 v138, 0xffffff79, v178
	v_max_i32_e32 v143, 0xffffff59, v178
	v_min_u32_e32 v170, 0x100, v170
	v_add_u32_e32 v136, 0x84, v136
	v_add_u32_e32 v137, 0xa4, v137
	v_add_u32_e32 v139, 0xa5, v139
	v_add_u32_e32 v141, 0xa6, v141
	v_add_u32_e32 v138, 0x87, v138
	v_add_u32_e32 v143, 0xa7, v143
	v_lshl_add_u32 v172, v170, 2, s57
	v_max_i32_e32 v170, 0xffffff76, v178
	v_min_u32_e32 v136, 0x100, v136
	v_min_u32_e32 v137, 0x100, v137
	v_min_u32_e32 v139, 0x100, v139
	v_min_u32_e32 v141, 0x100, v141
	v_min_u32_e32 v138, 0x100, v138
	v_min_u32_e32 v143, 0x100, v143
	v_add_u32_e32 v170, 0x8a, v170
	v_lshl_add_u32 v136, v136, 2, s57
	v_lshl_add_u32 v137, v137, 2, s57
	v_lshl_add_u32 v139, v139, 2, s57
	v_lshl_add_u32 v141, v141, 2, s57
	v_lshl_add_u32 v168, v138, 2, s57
	v_lshl_add_u32 v143, v143, 2, s57
	v_min_u32_e32 v170, 0x100, v170
	ds_read_b32 v136, v136
	ds_read_b32 v138, v137
	ds_read_b32 v137, v140
	ds_read_b32 v139, v139
	ds_read_b32 v140, v142
	ds_read_b32 v142, v141
	ds_read_b32 v141, v168
	ds_read_b32 v143, v143
	v_max_i32_e32 v168, 0xffffff78, v178
	v_max_i32_e32 v169, 0xffffff58, v178
	v_max_i32_e32 v171, 0xffffff57, v178
	v_max_i32_e32 v173, 0xffffff56, v178
	v_lshl_add_u32 v174, v170, 2, s57
	v_max_i32_e32 v170, 0xffffff75, v178
	v_max_i32_e32 v175, 0xffffff55, v178
	v_add_u32_e32 v168, 0x88, v168
	v_add_u32_e32 v169, 0xa8, v169
	v_add_u32_e32 v171, 0xa9, v171
	v_add_u32_e32 v173, 0xaa, v173
	v_add_u32_e32 v170, 0x8b, v170
	v_add_u32_e32 v175, 0xab, v175
	v_max_i32_e32 v182, 0xffffff53, v178
	v_max_i32_e32 v183, 0xffffff52, v178
	v_min_u32_e32 v168, 0x100, v168
	v_min_u32_e32 v169, 0x100, v169
	v_min_u32_e32 v171, 0x100, v171
	v_min_u32_e32 v173, 0x100, v173
	v_min_u32_e32 v170, 0x100, v170
	v_min_u32_e32 v175, 0x100, v175
	v_add_u32_e32 v182, 0xad, v182
	v_add_u32_e32 v183, 0xae, v183
	v_lshl_add_u32 v168, v168, 2, s57
	v_lshl_add_u32 v169, v169, 2, s57
	v_lshl_add_u32 v171, v171, 2, s57
	v_lshl_add_u32 v173, v173, 2, s57
	v_lshl_add_u32 v179, v170, 2, s57
	v_lshl_add_u32 v175, v175, 2, s57
	v_min_u32_e32 v182, 0x100, v182
	v_min_u32_e32 v183, 0x100, v183
	ds_read_b32 v168, v168
	ds_read_b32 v170, v169
	ds_read_b32 v169, v172
	ds_read_b32 v171, v171
	ds_read_b32 v172, v174
	ds_read_b32 v174, v173
	ds_read_b32 v173, v179
	ds_read_b32 v175, v175
	v_max_i32_e32 v179, 0xffffff74, v178
	v_max_i32_e32 v180, 0xffffff54, v178
	v_max_i32_e32 v181, 0xffffff73, v178
	v_lshl_add_u32 v186, v182, 2, s57
	v_max_i32_e32 v182, 0xffffff72, v178
	v_lshl_add_u32 v184, v183, 2, s57
	v_max_i32_e32 v183, 0xffffff71, v178
	v_max_i32_e32 v178, 0xffffff51, v178
	v_add_u32_e32 v179, 0x8c, v179
	v_add_u32_e32 v180, 0xac, v180
	v_add_u32_e32 v181, 0x8d, v181
	v_add_u32_e32 v182, 0x8e, v182
	v_add_u32_e32 v183, 0x8f, v183
	v_add_u32_e32 v178, 0xaf, v178
	v_min_u32_e32 v179, 0x100, v179
	v_min_u32_e32 v180, 0x100, v180
	v_min_u32_e32 v181, 0x100, v181
	v_min_u32_e32 v182, 0x100, v182
	v_min_u32_e32 v183, 0x100, v183
	v_min_u32_e32 v178, 0x100, v178
	v_lshl_add_u32 v179, v179, 2, s57
	v_lshl_add_u32 v180, v180, 2, s57
	v_lshl_add_u32 v181, v181, 2, s57
	v_lshl_add_u32 v182, v182, 2, s57
	v_lshl_add_u32 v183, v183, 2, s57
	v_lshl_add_u32 v185, v178, 2, s57
	ds_read_b32 v178, v179
	ds_read_b32 v180, v180
	ds_read_b32 v182, v182
	ds_read_b32 v183, v183
	ds_read_b32 v179, v181
	ds_read_b32 v185, v185
	ds_read_b32 v184, v184
	ds_read_b32 v181, v186
	s_waitcnt lgkmcnt(0)
	v_pk_add_f32 v[110:111], v[110:111], v[182:183]
	v_pk_add_f32 v[108:109], v[108:109], v[178:179]
	v_pk_add_f32 v[106:107], v[106:107], v[172:173]
	v_pk_add_f32 v[104:105], v[104:105], v[168:169]
	v_pk_add_f32 v[102:103], v[102:103], v[140:141]
	v_pk_add_f32 v[100:101], v[100:101], v[136:137]
	v_pk_add_f32 v[98:99], v[98:99], v[132:133]
	v_pk_add_f32 v[96:97], v[96:97], v[128:129]
	v_pk_add_f32 v[94:95], v[94:95], v[184:185]
	v_pk_add_f32 v[92:93], v[92:93], v[180:181]
	v_pk_add_f32 v[90:91], v[90:91], v[174:175]
	v_pk_add_f32 v[88:89], v[88:89], v[170:171]
	v_pk_add_f32 v[86:87], v[86:87], v[142:143]
	v_pk_add_f32 v[84:85], v[84:85], v[138:139]
	v_pk_add_f32 v[82:83], v[82:83], v[134:135]
	v_pk_add_f32 v[80:81], v[80:81], v[130:131]

.LBB0_704:
	v_add_u32_e32 v128, s56, v164
	s_waitcnt lgkmcnt(0)
	s_barrier
	v_add_u32_e32 v168, v128, v165
	ds_read_b128 v[140:143], v168 offset:18432
	ds_read_b128 v[132:135], v168 offset:18448
	ds_read_b128 v[136:139], v168 offset:23040
	ds_read_b128 v[128:131], v168 offset:23056
	ds_read_b128 v[178:181], v168 offset:27648
	ds_read_b128 v[182:185], v168 offset:27664
	ds_read_b128 v[186:189], v168 offset:32256
	ds_read_b128 v[190:193], v168 offset:32272
	v_exp_f32_e32 v96, v96
	v_exp_f32_e32 v97, v97
	v_exp_f32_e32 v98, v98
	v_exp_f32_e32 v99, v99
	v_exp_f32_e32 v100, v100
	v_exp_f32_e32 v101, v101
	v_exp_f32_e32 v102, v102
	v_exp_f32_e32 v103, v103
	v_exp_f32_e32 v104, v104
	v_exp_f32_e32 v105, v105
	v_exp_f32_e32 v106, v106
	v_exp_f32_e32 v107, v107
	v_exp_f32_e32 v108, v108
	v_exp_f32_e32 v109, v109
	v_exp_f32_e32 v110, v110
	v_exp_f32_e32 v111, v111
	v_cvt_pk_bf16_f32 v170, v96, v97
	v_cvt_pk_bf16_f32 v171, v98, v99
	v_cvt_pk_bf16_f32 v172, v100, v101
	v_cvt_pk_bf16_f32 v173, v102, v103
	v_cvt_pk_bf16_f32 v194, v104, v105
	v_cvt_pk_bf16_f32 v195, v106, v107
	v_cvt_pk_bf16_f32 v196, v108, v109
	v_cvt_pk_bf16_f32 v197, v110, v111
	s_waitcnt lgkmcnt(7)
	v_mfma_f32_32x32x16_bf16 v[48:63], v[140:143], v[170:173], v[48:63]
	v_exp_f32_e32 v80, v80
	v_exp_f32_e32 v81, v81
	v_exp_f32_e32 v82, v82
	v_exp_f32_e32 v83, v83
	s_waitcnt lgkmcnt(5)
	v_mfma_f32_32x32x16_bf16 v[0:15], v[136:139], v[170:173], v[0:15]
	v_mfma_f32_32x32x16_bf16 v[48:63], v[132:135], v[194:197], v[48:63]
	v_exp_f32_e32 v84, v84
	v_exp_f32_e32 v85, v85
	v_exp_f32_e32 v86, v86
	v_exp_f32_e32 v87, v87
	s_waitcnt lgkmcnt(4)
	v_mfma_f32_32x32x16_bf16 v[0:15], v[128:131], v[194:197], v[0:15]
	ds_read_b128 v[128:131], v168 offset:18496
	ds_read_b128 v[132:135], v168 offset:18512
	ds_read_b128 v[136:139], v168 offset:23104
	ds_read_b128 v[140:143], v168 offset:23120
	s_waitcnt lgkmcnt(7)
	v_mfma_f32_32x32x16_bf16 v[32:47], v[178:181], v[170:173], v[32:47]
	v_exp_f32_e32 v88, v88
	v_exp_f32_e32 v89, v89
	v_exp_f32_e32 v90, v90
	v_exp_f32_e32 v91, v91
	s_waitcnt lgkmcnt(5)
	v_mfma_f32_32x32x16_bf16 v[16:31], v[186:189], v[170:173], v[16:31]
	v_mfma_f32_32x32x16_bf16 v[32:47], v[182:185], v[194:197], v[32:47]
	v_exp_f32_e32 v92, v92
	v_exp_f32_e32 v93, v93
	v_exp_f32_e32 v94, v94
	v_exp_f32_e32 v95, v95
	v_cvt_pk_bf16_f32 v170, v80, v81
	v_cvt_pk_bf16_f32 v171, v82, v83
	v_cvt_pk_bf16_f32 v172, v84, v85
	s_waitcnt lgkmcnt(4)
	v_mfma_f32_32x32x16_bf16 v[16:31], v[190:193], v[194:197], v[16:31]
	v_cvt_pk_bf16_f32 v173, v86, v87
	v_cvt_pk_bf16_f32 v178, v88, v89
	v_cvt_pk_bf16_f32 v179, v90, v91
	v_cvt_pk_bf16_f32 v180, v92, v93
	v_cvt_pk_bf16_f32 v181, v94, v95
	ds_read_b128 v[182:185], v168 offset:27712
	ds_read_b128 v[186:189], v168 offset:27728
	ds_read_b128 v[190:193], v168 offset:32320
	ds_read_b128 v[194:197], v168 offset:32336
	s_cmp_gt_u32 s33, 29
	s_cselect_b64 s[60:61], -1, 0
	s_and_b64 vcc, exec, s[60:61]
	s_cbranch_vccnz .LBB0_706
	s_mul_i32 s62, s45, 0x9000
	s_or_b32 s63, s62, s35
	s_and_b64 s[58:59], s[54:55], exec
	s_cselect_b32 m0, s63, s82
	s_nop 0
	global_load_lds_dwordx4 v[240:241], off
	s_and_b64 s[58:59], s[10:11], exec
	s_cselect_b32 s58, s62, 0x12000
	s_add_i32 m0, s2, s58
	v_lshl_add_u64 v[240:241], v[240:241], 0, v[200:201]
	global_load_lds_dwordx4 v[242:243], off
	s_add_i32 s63, s62, s21
	s_and_b64 s[58:59], s[38:39], exec
	s_cselect_b32 m0, s63, s8
	v_lshl_add_u64 v[242:243], v[242:243], 0, v[202:203]
	global_load_lds_dwordx4 v[244:245], off
	s_and_b64 s[58:59], s[42:43], exec
	s_cselect_b32 s58, s62, 0x12000
	s_add_i32 m0, s26, s58
	v_lshl_add_u64 v[244:245], v[244:245], 0, v[204:205]
	global_load_lds_dwordx4 v[246:247], off
	s_add_i32 s62, s62, s3
	s_and_b64 s[58:59], s[50:51], exec
	s_cselect_b32 m0, s62, s9
	v_lshl_add_u64 v[246:247], v[246:247], 0, v[206:207]
	global_load_lds_dwordx4 v[248:249], off
	v_lshl_add_u64 v[248:249], v[248:249], 0, v[208:209]
.LBB0_706:
	s_waitcnt lgkmcnt(7)
	v_mfma_f32_32x32x16_bf16 v[48:63], v[128:131], v[170:173], v[48:63]
	v_add_f32_e32 v96, v97, v96
	v_add_f32_e32 v96, v98, v96
	v_add_f32_e32 v80, v81, v80
	v_add_f32_e32 v96, v99, v96
	s_waitcnt lgkmcnt(5)
	v_mfma_f32_32x32x16_bf16 v[0:15], v[136:139], v[170:173], v[0:15]
	v_add_f32_e32 v80, v82, v80
	v_add_f32_e32 v96, v100, v96
	v_add_f32_e32 v80, v83, v80
	v_add_f32_e32 v96, v101, v96
	v_mfma_f32_32x32x16_bf16 v[48:63], v[132:135], v[178:181], v[48:63]
	v_add_f32_e32 v80, v84, v80
	v_add_f32_e32 v96, v102, v96
	v_add_f32_e32 v80, v85, v80
	v_add_f32_e32 v96, v103, v96
	s_waitcnt lgkmcnt(4)
	v_mfma_f32_32x32x16_bf16 v[0:15], v[140:143], v[178:181], v[0:15]
	v_add_f32_e32 v80, v86, v80
	v_add_f32_e32 v96, v104, v96
	v_add_f32_e32 v80, v87, v80
	v_add_f32_e32 v96, v105, v96
	s_waitcnt lgkmcnt(3)
	v_mfma_f32_32x32x16_bf16 v[32:47], v[182:185], v[170:173], v[32:47]
	v_add_f32_e32 v80, v88, v80
	v_add_f32_e32 v96, v106, v96
	v_add_f32_e32 v80, v89, v80
	v_add_f32_e32 v96, v107, v96
	s_waitcnt lgkmcnt(1)
	v_mfma_f32_32x32x16_bf16 v[16:31], v[190:193], v[170:173], v[16:31]
	v_add_f32_e32 v80, v90, v80
	v_add_f32_e32 v96, v108, v96
	v_add_f32_e32 v80, v91, v80
	v_add_f32_e32 v96, v109, v96
	v_mfma_f32_32x32x16_bf16 v[32:47], v[186:189], v[178:181], v[32:47]
	v_add_f32_e32 v80, v92, v80
	v_add_f32_e32 v96, v110, v96
	v_add_f32_e32 v80, v93, v80
	v_add_f32_e32 v96, v111, v96
	s_waitcnt lgkmcnt(0)
	v_mfma_f32_32x32x16_bf16 v[16:31], v[194:197], v[178:181], v[16:31]
	v_add_f32_e32 v80, v94, v80
	v_add_f32_e32 v96, v157, v96
	v_add_f32_e32 v80, v95, v80
	v_add_f32_e32 v157, v96, v80
	s_mov_b64 s[62:63], -1
	s_and_b64 vcc, exec, s[60:61]
	s_cbranch_vccz .LBB0_708
	s_waitcnt vmcnt(0) lgkmcnt(0)
	s_barrier
	s_mov_b64 s[62:63], 0
